# P3: every CU runs its attention units first and its sample-attention/spatial-gate units after them (staggered arrival at the memory-bound part)
# speedup vs baseline: 1.0071x; 1.0037x over previous
; #define LAS __attribute__((address_space(3)))
; #define FRESH() const int lane = fresh_lane(); const int tid = wave * 64 + lane; (void)tid
; #define REPS(k) _Pragma("nounroll") for (int rep_ = 0, nrep_ = opaque_i(((PROBE_REP >> (k)) & 1) ? 2 : 1); rep_ < nrep_; ++rep_)
; __global__ void __launch_bounds__(NTHR, 2) fwd_megakernel(Args args) {
;     ...
;         LAS float* bt = (LAS float*)(lds + BT_OFF);
;         __syncthreads();
;         { FRESH(); bias_table(args, bt, tid); }
;         __syncthreads();
;         REPS(10) for (int v = vcu; v < 256; v += G) {
;     ...
;             { FRESH(); sattn_unit(args, lds, bt, v >> 4, (v >> 1) & 7, v & 1, tid, wave, lane); }
;             { FRESH(); sgate_unit(args, lds, v, tid, wave, lane); } if (v >= 240) { FRESH(); sgate_unit(args, lds, 256 + (v - 240), tid, wave, lane); }
;     ...
;         }
;         __syncthreads();
;         REPS(11) for (int v = vcu; v < 256; v += G) {
.LBB0_289:
	s_or_b64 exec, exec, s[4:5]
	s_mov_b32 s0, 1
	s_waitcnt lgkmcnt(0)
	s_barrier
	s_cmp_lt_i32 s0, 1
	v_writelane_b32 v251, s0, 43
	v_writelane_b32 v251, s75, 40
	s_cbranch_scc1 .LBB0_365
	v_readlane_b32 s0, v251, 9
	s_mov_b32 s1, 0
	s_cmp_eq_u32 s0, s0
	v_writelane_b32 v251, s1, 62
	s_cbranch_scc0 .Lp3_small_entry
	s_mov_b32 s1, 1
	s_nop 0
	v_writelane_b32 v251, s1, 62
	v_writelane_b32 v251, s11, 50
	v_writelane_b32 v251, s22, 51
	v_writelane_b32 v251, s23, 52
	v_writelane_b32 v251, s40, 53
	v_writelane_b32 v251, s41, 54
	v_writelane_b32 v251, s42, 55
	v_writelane_b32 v251, s43, 56
	v_writelane_b32 v251, s52, 57
	v_writelane_b32 v251, s53, 58
	v_writelane_b32 v251, s54, 59
	v_writelane_b32 v251, s55, 60
	v_writelane_b32 v251, s56, 61
	v_writelane_b32 v251, s57, 63
	s_branch .LBB0_365
